# MLA loop: stage DMA pieces issued after the 12th (last) S^T MFMA of step A, in the VALU region before PV, instead of after the 2nd
# baseline (speedup 1.0000x reference)
.LBB0_859:
	ds_read_b128 v[236:239], v214 offset:8192
	ds_read_b128 v[240:243], v215 offset:8192
	ds_read_b128 v[244:247], v216 offset:8192
	ds_read_b128 v[248:251], v217 offset:8192
	ds_read_b128 v[252:255], v218 offset:8192
	ds_read_b128 v[176:179], v219 offset:8192
	v_exp_f32_e32 v97, v97
	v_exp_f32_e32 v99, v99
	v_exp_f32_e32 v100, v100
	v_exp_f32_e32 v101, v101
	v_exp_f32_e32 v102, v102
	v_exp_f32_e32 v103, v103
	v_exp_f32_e32 v106, v106
	v_exp_f32_e32 v107, v107
	s_waitcnt lgkmcnt(4)
	v_mfma_f32_32x32x16_bf16 v[80:95], v[236:239], v[144:147], v[64:79]
	ds_read_b128 v[180:183], v220 offset:8192
	v_exp_f32_e32 v108, v108
	v_exp_f32_e32 v109, v109
	v_exp_f32_e32 v110, v110
	v_exp_f32_e32 v111, v111
	v_mfma_f32_32x32x16_bf16 v[80:95], v[240:243], v[156:159], v[80:95]
	ds_read_b128 v[236:239], v221 offset:8192
	s_waitcnt lgkmcnt(4)
	v_mfma_f32_32x32x16_bf16 v[80:95], v[244:247], v[168:171], v[80:95]
	ds_read_b128 v[240:243], v205 offset:53248
	v_mfma_f32_32x32x16_bf16 v[80:95], v[248:251], v[172:175], v[80:95]
	ds_read_b128 v[244:247], v207 offset:53248
	s_waitcnt lgkmcnt(4)
	v_mfma_f32_32x32x16_bf16 v[80:95], v[252:255], v[164:167], v[80:95]
	ds_read_b128 v[248:251], v209 offset:53248
	v_mfma_f32_32x32x16_bf16 v[80:95], v[176:179], v[160:163], v[80:95]
	ds_read_b128 v[252:255], v211 offset:53248
	s_waitcnt lgkmcnt(4)
	v_mfma_f32_32x32x16_bf16 v[80:95], v[180:183], v[152:155], v[80:95]
	ds_read_b128 v[176:179], v225
	v_mfma_f32_32x32x16_bf16 v[80:95], v[236:239], v[148:151], v[80:95]
	ds_read_b128 v[180:183], v225 offset:4096
	s_waitcnt lgkmcnt(4)
	v_mfma_f32_32x32x16_bf16 v[80:95], v[240:243], v[140:143], v[80:95]
	ds_read_b128 v[236:239], v225 offset:8192
	v_mfma_f32_32x32x16_bf16 v[80:95], v[244:247], v[136:139], v[80:95]
	ds_read_b128 v[240:243], v225 offset:12288
	s_waitcnt lgkmcnt(4)
	v_mfma_f32_32x32x16_bf16 v[80:95], v[248:251], v[132:135], v[80:95]
	ds_read_b128 v[244:247], v226
	v_mfma_f32_32x32x16_bf16 v[80:95], v[252:255], v[128:131], v[80:95]
	ds_read_b128 v[248:251], v226 offset:4096
	s_add_u32 s98, s34, s60
	s_addc_u32 s99, s35, s59
	s_add_u32 s98, s98, 0x140fc000
	s_addc_u32 s99, s99, 0
	s_add_u32 s100, s34, s62
	s_addc_u32 s101, s35, s61
	s_add_u32 s100, s100, 0x171b0100
	s_addc_u32 s101, s101, 0
	s_mov_b32 m0, s52
	s_cmp_lg_u64 s[24:25], 0
	s_cselect_b32 s4, s100, s98
	s_cselect_b32 s5, s101, s99
	global_load_lds_dwordx4 v190, s[4:5]
	s_mov_b32 m0, s53
	s_cmp_lg_u64 s[26:27], 0
	s_cselect_b32 s4, s100, s98
	s_cselect_b32 s5, s101, s99
	global_load_lds_dwordx4 v192, s[4:5]
	s_mov_b32 m0, s54
	s_cmp_lg_u64 s[28:29], 0
	s_cselect_b32 s4, s100, s98
	s_cselect_b32 s5, s101, s99
	global_load_lds_dwordx4 v194, s[4:5]
	s_mov_b32 m0, s55
	s_cmp_lg_u64 s[30:31], 0
	s_cselect_b32 s4, s100, s98
	s_cselect_b32 s5, s101, s99
	global_load_lds_dwordx4 v196, s[4:5]
	s_mov_b32 m0, s56
	s_cmp_lg_u64 s[6:7], 0
	s_cselect_b32 s4, s100, s98
	s_cselect_b32 s5, s101, s99
	global_load_lds_dwordx4 v198, s[4:5]
	v_exp_f32_e32 v112, v96
	v_exp_f32_e32 v113, v98
	v_exp_f32_e32 v114, v104
	v_exp_f32_e32 v115, v105
	v_add_f32_e32 v96, 0, v112
	v_add_f32_e32 v96, v97, v96
	v_add_f32_e32 v96, v113, v96
	v_add_f32_e32 v96, v99, v96
	v_add_f32_e32 v96, v100, v96
	v_add_f32_e32 v96, v101, v96
	v_add_f32_e32 v96, v102, v96
	v_add_f32_e32 v96, v103, v96
	v_cvt_pk_bf16_f32 v100, v100, v101
	v_cvt_pk_bf16_f32 v101, v102, v103
	v_cvt_pk_bf16_f32 v98, v112, v97
	v_cvt_pk_bf16_f32 v99, v113, v99
	v_max_f32_e32 v97, v81, v81
	v_add_f32_e32 v96, v114, v96
	s_waitcnt lgkmcnt(4)
	v_mfma_f32_32x32x16_bf16 v[48:63], v[176:179], v[98:101], v[48:63]
	ds_read_b128 v[252:255], v226 offset:8192
	v_add_f32_e32 v96, v115, v96
	v_add_f32_e32 v96, v106, v96
	v_add_f32_e32 v96, v107, v96
	v_add_f32_e32 v96, v108, v96
	v_add_f32_e32 v96, v109, v96
	v_add_f32_e32 v96, v110, v96
	v_mfma_f32_32x32x16_bf16 v[32:47], v[180:183], v[98:101], v[32:47]
	ds_read_b128 v[176:179], v226 offset:12288
	v_add_f32_e32 v96, v111, v96
	v_add_f32_e32 v112, v230, v96
	s_waitcnt lgkmcnt(4)
	v_mfma_f32_32x32x16_bf16 v[16:31], v[236:239], v[98:101], v[16:31]
	ds_read_b128 v[180:183], v214 offset:16384
	v_mfma_f32_32x32x16_bf16 v[0:15], v[240:243], v[98:101], v[0:15]
	ds_read_b128 v[236:239], v215 offset:16384
	v_cvt_pk_bf16_f32 v98, v114, v115
	v_cvt_pk_bf16_f32 v99, v106, v107
	v_cvt_pk_bf16_f32 v100, v108, v109
	v_cvt_pk_bf16_f32 v101, v110, v111
	s_nop 0
	s_waitcnt lgkmcnt(4)
	v_mfma_f32_32x32x16_bf16 v[48:63], v[244:247], v[98:101], v[48:63]
	ds_read_b128 v[240:243], v216 offset:16384
	v_mfma_f32_32x32x16_bf16 v[32:47], v[248:251], v[98:101], v[32:47]
	ds_read_b128 v[244:247], v217 offset:16384
	s_waitcnt lgkmcnt(4)
	v_mfma_f32_32x32x16_bf16 v[16:31], v[252:255], v[98:101], v[16:31]
	ds_read_b128 v[248:251], v218 offset:16384
	v_mfma_f32_32x32x16_bf16 v[0:15], v[176:179], v[98:101], v[0:15]
	ds_read_b128 v[252:255], v219 offset:16384
	v_max_f32_e32 v98, v80, v80
	v_max_f32_e32 v97, v98, v97
	v_max3_f32 v97, v97, v82, v83
	v_max3_f32 v97, v97, v84, v85
	v_max3_f32 v97, v97, v86, v87
	v_max3_f32 v97, v97, v88, v89
	v_max3_f32 v97, v97, v90, v91
	v_max3_f32 v97, v97, v92, v93
	v_max3_f32 v97, v97, v94, v95
	ds_bpermute_b32 v98, v229, v97
	s_waitcnt lgkmcnt(0)
	v_max_f32_e32 v96, v98, v98
	v_max_f32_e32 v96, v97, v96
	v_cmp_lt_f32_e32 vcc, 0, v96
	s_cbranch_vccz .LBB0_861
	v_max_f32_e32 v96, v96, v96
	v_max_f32_e32 v96, 0, v96
	v_exp_f32_e64 v98, -v96
	v_pk_add_f32 v[80:81], v[80:81], v[96:97] op_sel_hi:[1,0] neg_lo:[0,1] neg_hi:[0,1]
	v_pk_add_f32 v[82:83], v[82:83], v[96:97] op_sel_hi:[1,0] neg_lo:[0,1] neg_hi:[0,1]
	v_pk_add_f32 v[84:85], v[84:85], v[96:97] op_sel_hi:[1,0] neg_lo:[0,1] neg_hi:[0,1]
	v_mul_f32_e32 v112, v112, v98
	v_pk_add_f32 v[86:87], v[86:87], v[96:97] op_sel_hi:[1,0] neg_lo:[0,1] neg_hi:[0,1]
	v_pk_add_f32 v[88:89], v[88:89], v[96:97] op_sel_hi:[1,0] neg_lo:[0,1] neg_hi:[0,1]
	v_pk_add_f32 v[90:91], v[90:91], v[96:97] op_sel_hi:[1,0] neg_lo:[0,1] neg_hi:[0,1]
	v_pk_add_f32 v[92:93], v[92:93], v[96:97] op_sel_hi:[1,0] neg_lo:[0,1] neg_hi:[0,1]
	v_sub_f32_e32 v79, v79, v96
	v_sub_f32_e32 v78, v78, v96
	v_sub_f32_e32 v77, v77, v96
	v_sub_f32_e32 v76, v76, v96
	v_sub_f32_e32 v75, v75, v96
	v_sub_f32_e32 v74, v74, v96
	v_sub_f32_e32 v73, v73, v96
	v_sub_f32_e32 v72, v72, v96
	v_sub_f32_e32 v71, v71, v96
	v_sub_f32_e32 v70, v70, v96
	v_sub_f32_e32 v69, v69, v96
	v_sub_f32_e32 v68, v68, v96
	v_sub_f32_e32 v67, v67, v96
	v_sub_f32_e32 v66, v66, v96
	v_sub_f32_e32 v65, v65, v96
	v_sub_f32_e32 v64, v64, v96
	v_pk_add_f32 v[94:95], v[94:95], v[96:97] op_sel_hi:[1,0] neg_lo:[0,1] neg_hi:[0,1]
	v_pk_mul_f32 v[62:63], v[62:63], v[98:99] op_sel_hi:[1,0]
	v_pk_mul_f32 v[60:61], v[60:61], v[98:99] op_sel_hi:[1,0]
	v_pk_mul_f32 v[58:59], v[58:59], v[98:99] op_sel_hi:[1,0]
	v_pk_mul_f32 v[56:57], v[56:57], v[98:99] op_sel_hi:[1,0]
	v_pk_mul_f32 v[54:55], v[54:55], v[98:99] op_sel_hi:[1,0]
	v_pk_mul_f32 v[52:53], v[52:53], v[98:99] op_sel_hi:[1,0]
	v_pk_mul_f32 v[50:51], v[50:51], v[98:99] op_sel_hi:[1,0]
	v_pk_mul_f32 v[48:49], v[48:49], v[98:99] op_sel_hi:[1,0]
	v_pk_mul_f32 v[46:47], v[46:47], v[98:99] op_sel_hi:[1,0]
	v_pk_mul_f32 v[44:45], v[44:45], v[98:99] op_sel_hi:[1,0]
	v_pk_mul_f32 v[42:43], v[42:43], v[98:99] op_sel_hi:[1,0]
	v_pk_mul_f32 v[40:41], v[40:41], v[98:99] op_sel_hi:[1,0]
	v_pk_mul_f32 v[38:39], v[38:39], v[98:99] op_sel_hi:[1,0]
	v_pk_mul_f32 v[36:37], v[36:37], v[98:99] op_sel_hi:[1,0]
	v_pk_mul_f32 v[34:35], v[34:35], v[98:99] op_sel_hi:[1,0]
	v_pk_mul_f32 v[32:33], v[32:33], v[98:99] op_sel_hi:[1,0]
	v_pk_mul_f32 v[30:31], v[30:31], v[98:99] op_sel_hi:[1,0]
	v_pk_mul_f32 v[28:29], v[28:29], v[98:99] op_sel_hi:[1,0]
	v_pk_mul_f32 v[26:27], v[26:27], v[98:99] op_sel_hi:[1,0]
	v_pk_mul_f32 v[24:25], v[24:25], v[98:99] op_sel_hi:[1,0]
	v_pk_mul_f32 v[22:23], v[22:23], v[98:99] op_sel_hi:[1,0]
	v_pk_mul_f32 v[20:21], v[20:21], v[98:99] op_sel_hi:[1,0]
	v_pk_mul_f32 v[18:19], v[18:19], v[98:99] op_sel_hi:[1,0]
	v_pk_mul_f32 v[16:17], v[16:17], v[98:99] op_sel_hi:[1,0]
	v_pk_mul_f32 v[14:15], v[14:15], v[98:99] op_sel_hi:[1,0]
	v_pk_mul_f32 v[12:13], v[12:13], v[98:99] op_sel_hi:[1,0]
	v_pk_mul_f32 v[10:11], v[10:11], v[98:99] op_sel_hi:[1,0]
	v_pk_mul_f32 v[8:9], v[8:9], v[98:99] op_sel_hi:[1,0]
	v_pk_mul_f32 v[6:7], v[6:7], v[98:99] op_sel_hi:[1,0]
	v_pk_mul_f32 v[4:5], v[4:5], v[98:99] op_sel_hi:[1,0]
	v_pk_mul_f32 v[2:3], v[2:3], v[98:99] op_sel_hi:[1,0]
	v_pk_mul_f32 v[0:1], v[0:1], v[98:99] op_sel_hi:[1,0]

.LBB0_863:
	v_exp_f32_e32 v96, v96
	v_exp_f32_e32 v97, v97
	v_exp_f32_e32 v98, v98
	v_mfma_f32_32x32x16_bf16 v[80:95], v[176:179], v[144:147], v[64:79]
	ds_read_b128 v[252:255], v220 offset:24576
	v_exp_f32_e32 v99, v99
	v_exp_f32_e32 v100, v100
	v_exp_f32_e32 v101, v101
	v_exp_f32_e32 v102, v102
	v_exp_f32_e32 v103, v103
	v_cvt_pk_bf16_f32 v122, v96, v97
	v_cvt_pk_bf16_f32 v123, v98, v99
	v_mfma_f32_32x32x16_bf16 v[80:95], v[180:183], v[156:159], v[80:95]
	ds_read_b128 v[176:179], v221 offset:24576
	v_cvt_pk_bf16_f32 v124, v100, v101
	v_cvt_pk_bf16_f32 v125, v102, v103
	v_exp_f32_e32 v104, v104
	v_exp_f32_e32 v105, v105
	v_exp_f32_e32 v106, v106
	v_exp_f32_e32 v107, v107
	v_mfma_f32_32x32x16_bf16 v[80:95], v[236:239], v[168:171], v[80:95]
	ds_read_b128 v[180:183], v205 offset:61440
	v_exp_f32_e32 v108, v108
	v_exp_f32_e32 v109, v109
	v_exp_f32_e32 v110, v110
	v_exp_f32_e32 v111, v111
	s_add_i32 s16, s8, 3
	s_cmp_lt_u32 s16, s9
	s_cselect_b64 s[10:11], -1, 0
	s_waitcnt lgkmcnt(4)
	v_mfma_f32_32x32x16_bf16 v[80:95], v[240:243], v[172:175], v[80:95]
	ds_read_b128 v[236:239], v207 offset:61440
	s_cmp_ge_u32 s16, s9
	v_mfma_f32_32x32x16_bf16 v[80:95], v[244:247], v[164:167], v[80:95]
	ds_read_b128 v[240:243], v209 offset:61440
	s_waitcnt lgkmcnt(4)
	v_mfma_f32_32x32x16_bf16 v[80:95], v[248:251], v[160:163], v[80:95]
	ds_read_b128 v[244:247], v211 offset:61440
	v_mfma_f32_32x32x16_bf16 v[80:95], v[252:255], v[152:155], v[80:95]
	ds_read_b128 v[248:251], v225 offset:16384
	s_waitcnt lgkmcnt(4)
	v_mfma_f32_32x32x16_bf16 v[80:95], v[176:179], v[148:151], v[80:95]
	ds_read_b128 v[252:255], v225 offset:20480
	v_mfma_f32_32x32x16_bf16 v[80:95], v[180:183], v[140:143], v[80:95]
	ds_read_b128 v[176:179], v225 offset:24576
	s_waitcnt lgkmcnt(4)
	v_mfma_f32_32x32x16_bf16 v[80:95], v[236:239], v[136:139], v[80:95]
	ds_read_b128 v[180:183], v225 offset:28672
	v_mfma_f32_32x32x16_bf16 v[80:95], v[240:243], v[132:135], v[80:95]
	ds_read_b128 v[236:239], v226 offset:16384
	s_waitcnt lgkmcnt(4)
	v_mfma_f32_32x32x16_bf16 v[80:95], v[244:247], v[128:131], v[80:95]
	ds_read_b128 v[240:243], v226 offset:20480
	s_add_i32 s4, s8, 3
	s_cmp_ge_u32 s4, s9
	s_cbranch_scc1 .Lmla_dma_skip_t1
	s_add_u32 s98, s34, s60
	s_addc_u32 s99, s35, s59
	s_add_u32 s98, s98, 0x14102000
	s_addc_u32 s99, s99, 0
	s_add_u32 s100, s34, s62
	s_addc_u32 s101, s35, s61
	s_add_u32 s100, s100, 0x171b0180
	s_addc_u32 s101, s101, 0
	s_mov_b32 m0, s41
	s_cmp_lg_u64 s[24:25], 0
	s_cselect_b32 s4, s100, s98
	s_cselect_b32 s5, s101, s99
	global_load_lds_dwordx4 v190, s[4:5]
	s_mov_b32 m0, s42
	s_cmp_lg_u64 s[26:27], 0
	s_cselect_b32 s4, s100, s98
	s_cselect_b32 s5, s101, s99
	global_load_lds_dwordx4 v192, s[4:5]
	s_mov_b32 m0, s43
	s_cmp_lg_u64 s[28:29], 0
	s_cselect_b32 s4, s100, s98
	s_cselect_b32 s5, s101, s99
	global_load_lds_dwordx4 v194, s[4:5]
	s_mov_b32 m0, s44
	s_cmp_lg_u64 s[30:31], 0
	s_cselect_b32 s4, s100, s98
	s_cselect_b32 s5, s101, s99
	global_load_lds_dwordx4 v196, s[4:5]
	s_mov_b32 m0, s45
	s_cmp_lg_u64 s[6:7], 0
	s_cselect_b32 s4, s100, s98
	s_cselect_b32 s5, s101, s99
	global_load_lds_dwordx4 v198, s[4:5]
.Lmla_dma_skip_t1:
	v_mfma_f32_32x32x16_bf16 v[48:63], v[248:251], v[122:125], v[48:63]
	ds_read_b128 v[244:247], v226 offset:24576
	s_nop 8
	v_max_f32_e32 v113, v81, v81
	v_max_f32_e32 v126, v80, v80
	v_max_f32_e32 v113, v126, v113
	v_max3_f32 v113, v113, v82, v83
	v_max3_f32 v113, v113, v84, v85
	v_max3_f32 v113, v113, v86, v87
	v_max3_f32 v113, v113, v88, v89
	s_waitcnt lgkmcnt(4)
	v_mfma_f32_32x32x16_bf16 v[32:47], v[252:255], v[122:125], v[32:47]
	ds_read_b128 v[248:251], v226 offset:28672
	v_max3_f32 v113, v113, v90, v91
	v_max3_f32 v113, v113, v92, v93
	v_max3_f32 v113, v113, v94, v95
	v_mfma_f32_32x32x16_bf16 v[16:31], v[176:179], v[122:125], v[16:31]
	ds_read_b128 v[252:255], v214 offset:32768
	s_waitcnt lgkmcnt(4)
	v_mfma_f32_32x32x16_bf16 v[0:15], v[180:183], v[122:125], v[0:15]
	ds_read_b128 v[176:179], v215 offset:32768
	v_cvt_pk_bf16_f32 v118, v104, v105
	v_cvt_pk_bf16_f32 v119, v106, v107
	v_cvt_pk_bf16_f32 v120, v108, v109
	v_cvt_pk_bf16_f32 v121, v110, v111
	s_nop 0
	s_nop 0
	v_mfma_f32_32x32x16_bf16 v[48:63], v[236:239], v[118:121], v[48:63]
	ds_read_b128 v[180:183], v216 offset:32768
	s_waitcnt lgkmcnt(4)
	v_mfma_f32_32x32x16_bf16 v[32:47], v[240:243], v[118:121], v[32:47]
	ds_read_b128 v[236:239], v217 offset:32768
	v_mfma_f32_32x32x16_bf16 v[16:31], v[244:247], v[118:121], v[16:31]
	ds_read_b128 v[240:243], v218 offset:32768
	ds_bpermute_b32 v114, v229, v113
	s_waitcnt lgkmcnt(5)
	v_mfma_f32_32x32x16_bf16 v[0:15], v[248:251], v[118:121], v[0:15]
	ds_read_b128 v[244:247], v219 offset:32768

.LBB0_869:
	v_exp_f32_e32 v96, v96
	v_exp_f32_e32 v97, v97
	v_exp_f32_e32 v98, v98
	v_mfma_f32_32x32x16_bf16 v[80:95], v[248:251], v[144:147], v[64:79]
	ds_read_b128 v[244:247], v220 offset:40960
	v_exp_f32_e32 v99, v99
	v_exp_f32_e32 v100, v100
	v_exp_f32_e32 v101, v101
	v_exp_f32_e32 v102, v102
	v_exp_f32_e32 v103, v103
	v_cvt_pk_bf16_f32 v122, v96, v97
	v_cvt_pk_bf16_f32 v123, v98, v99
	v_mfma_f32_32x32x16_bf16 v[80:95], v[252:255], v[156:159], v[80:95]
	ds_read_b128 v[248:251], v221 offset:40960
	v_cvt_pk_bf16_f32 v124, v100, v101
	v_cvt_pk_bf16_f32 v125, v102, v103
	v_exp_f32_e32 v104, v104
	v_exp_f32_e32 v105, v105
	v_exp_f32_e32 v106, v106
	v_exp_f32_e32 v107, v107
	v_mfma_f32_32x32x16_bf16 v[80:95], v[176:179], v[168:171], v[80:95]
	ds_read_b128 v[252:255], v206 offset:20480
	v_exp_f32_e32 v108, v108
	v_exp_f32_e32 v109, v109
	v_exp_f32_e32 v110, v110
	v_exp_f32_e32 v111, v111
	s_add_i32 s4, s8, 4
	s_cmp_ge_u32 s4, s9
	s_waitcnt lgkmcnt(4)
	v_mfma_f32_32x32x16_bf16 v[80:95], v[180:183], v[172:175], v[80:95]
	ds_read_b128 v[176:179], v208 offset:20480
	v_mfma_f32_32x32x16_bf16 v[80:95], v[236:239], v[164:167], v[80:95]
	ds_read_b128 v[180:183], v210 offset:20480
	s_waitcnt lgkmcnt(4)
	v_mfma_f32_32x32x16_bf16 v[80:95], v[240:243], v[160:163], v[80:95]
	ds_read_b128 v[236:239], v212 offset:20480
	v_mfma_f32_32x32x16_bf16 v[80:95], v[244:247], v[152:155], v[80:95]
	ds_read_b128 v[240:243], v225 offset:32768
	s_waitcnt lgkmcnt(4)
	v_mfma_f32_32x32x16_bf16 v[80:95], v[248:251], v[148:151], v[80:95]
	ds_read_b128 v[244:247], v225 offset:36864
	v_mfma_f32_32x32x16_bf16 v[80:95], v[252:255], v[140:143], v[80:95]
	ds_read_b128 v[248:251], v225 offset:40960
	s_waitcnt lgkmcnt(4)
	v_mfma_f32_32x32x16_bf16 v[80:95], v[176:179], v[136:139], v[80:95]
	ds_read_b128 v[252:255], v225 offset:45056
	v_mfma_f32_32x32x16_bf16 v[80:95], v[180:183], v[132:135], v[80:95]
	ds_read_b128 v[176:179], v226 offset:32768
	s_waitcnt lgkmcnt(4)
	v_mfma_f32_32x32x16_bf16 v[80:95], v[236:239], v[128:131], v[80:95]
	ds_read_b128 v[180:183], v226 offset:36864
	s_add_i32 s4, s8, 4
	s_cmp_ge_u32 s4, s9
	s_cbranch_scc1 .Lmla_dma_skip_t2
	s_add_u32 s98, s34, s60
	s_addc_u32 s99, s35, s59
	s_add_u32 s98, s98, 0x14108000
	s_addc_u32 s99, s99, 0
	s_add_u32 s100, s34, s62
	s_addc_u32 s101, s35, s61
	s_add_u32 s100, s100, 0x171b0200
	s_addc_u32 s101, s101, 0
	s_mov_b32 m0, s46
	s_cmp_lg_u64 s[24:25], 0
	s_cselect_b32 s4, s100, s98
	s_cselect_b32 s5, s101, s99
	global_load_lds_dwordx4 v190, s[4:5]
	s_mov_b32 m0, s47
	s_cmp_lg_u64 s[26:27], 0
	s_cselect_b32 s4, s100, s98
	s_cselect_b32 s5, s101, s99
	global_load_lds_dwordx4 v192, s[4:5]
	s_mov_b32 m0, s48
	s_cmp_lg_u64 s[28:29], 0
	s_cselect_b32 s4, s100, s98
	s_cselect_b32 s5, s101, s99
	global_load_lds_dwordx4 v194, s[4:5]
	s_mov_b32 m0, s49
	s_cmp_lg_u64 s[30:31], 0
	s_cselect_b32 s4, s100, s98
	s_cselect_b32 s5, s101, s99
	global_load_lds_dwordx4 v196, s[4:5]
	s_mov_b32 m0, s50
	s_cmp_lg_u64 s[6:7], 0
	s_cselect_b32 s4, s100, s98
	s_cselect_b32 s5, s101, s99
	global_load_lds_dwordx4 v198, s[4:5]
.Lmla_dma_skip_t2:
	v_mfma_f32_32x32x16_bf16 v[48:63], v[240:243], v[122:125], v[48:63]
	ds_read_b128 v[236:239], v226 offset:40960
	s_nop 8
	v_max_f32_e32 v113, v81, v81
	v_max_f32_e32 v126, v80, v80
	v_max_f32_e32 v113, v126, v113
	v_max3_f32 v113, v113, v82, v83
	v_max3_f32 v113, v113, v84, v85
	v_max3_f32 v113, v113, v86, v87
	v_max3_f32 v113, v113, v88, v89
	s_waitcnt lgkmcnt(4)
	v_mfma_f32_32x32x16_bf16 v[32:47], v[244:247], v[122:125], v[32:47]
	ds_read_b128 v[240:243], v226 offset:45056
	v_max3_f32 v113, v113, v90, v91
	v_max3_f32 v113, v113, v92, v93
	v_max3_f32 v113, v113, v94, v95
	v_mfma_f32_32x32x16_bf16 v[16:31], v[248:251], v[122:125], v[16:31]
	ds_read_b128 v[244:247], v214
	s_waitcnt lgkmcnt(4)
	v_mfma_f32_32x32x16_bf16 v[0:15], v[252:255], v[122:125], v[0:15]
	ds_read_b128 v[248:251], v215
	v_cvt_pk_bf16_f32 v118, v104, v105
	v_cvt_pk_bf16_f32 v119, v106, v107
	v_cvt_pk_bf16_f32 v120, v108, v109
	v_cvt_pk_bf16_f32 v121, v110, v111
	s_nop 0
	s_nop 0
	v_mfma_f32_32x32x16_bf16 v[48:63], v[176:179], v[118:121], v[48:63]
	ds_read_b128 v[252:255], v216
	s_waitcnt lgkmcnt(4)
	v_mfma_f32_32x32x16_bf16 v[32:47], v[180:183], v[118:121], v[32:47]
	ds_read_b128 v[176:179], v217
	v_mfma_f32_32x32x16_bf16 v[16:31], v[236:239], v[118:121], v[16:31]
	ds_read_b128 v[180:183], v218
	ds_bpermute_b32 v114, v229, v113
	s_waitcnt lgkmcnt(5)
	v_mfma_f32_32x32x16_bf16 v[0:15], v[240:243], v[118:121], v[0:15]
	ds_read_b128 v[236:239], v219
